# v54 plus nt on mc_item<0/1> Y stores
# speedup vs baseline: 1.0071x; 1.0014x over previous
; #define BSYNC() do { asm volatile("s_waitcnt vmcnt(0) lgkmcnt(0)" ::: "memory"); __syncthreads(); } while (0)
; template <int TY> __device__ __forceinline__ void mc_item(const Params& p, ldsp lds, int item) {
;     ...
;     BSYNC();
; #pragma unroll
;     for (int tk = 0; tk < 4; ++tk) { float s = 0.f;
; #pragma unroll
;         for (int w = 0; w < 8; ++w) s += RED[w * 64 + 16 * tk + l15];
;         rstd[tk] = rsqrtf(s * (1.0f / DV) + EPS); }
;     const float* nwp = TY == 0 ? p.in[12] : (TY == 1 ? p.in[14] : p.in[17]);
;     const int goff = TY == 0 ? E_RA + h * 128 : (TY == 1 ? E_GB + h * 128 : O_G + h * 512);
;     constexpr int LDY = TY == 2 ? 2048 : 1024; const int ycol = TY == 0 ? h * 128 : (TY == 1 ? 512 + h * 128 : h * 512);
;     bf16_t* Y = (bf16_t*)(p.ws + WS_Y);
; #pragma unroll
;     for (int ei = 0; ei < ET; ++ei) { const int e0 = 16 * (wave * ET + ei) + 4 * q4; const f32x4 w4 = *(const f32x4*)(nwp + e0);
; #pragma unroll
;         for (int tk = 0; tk < 4; ++tk) { const size_t row = (size_t)row0 + 16 * tk + l15;
;             const u32x2 gw = *(const u32x2*)(Pb + row * PP + goff + e0);
.LBB0_1239:
	s_or_b64 exec, exec, s[0:1]
	s_lshl_b32 s9, s15, 1
	s_add_u32 s0, s26, s9
	v_or_b32_e32 v18, s12, v28
	s_addc_u32 s1, s27, 0
	v_or_b32_e32 v22, s16, v30
	s_waitcnt lgkmcnt(0)
	v_ashrrev_i32_e32 v19, 31, v18
	v_mov_b64_e32 v[28:29], s[0:1]
	v_lshlrev_b64 v[26:27], 1, v[18:19]
	v_mad_i64_i32 v[24:25], s[0:1], v22, s55, v[28:29]
	v_lshl_add_u64 v[24:25], v[24:25], 0, v[26:27]
	s_waitcnt vmcnt(0) lgkmcnt(0)
	s_barrier
	global_load_dwordx2 v[48:49], v[24:25], off offset:2048
	v_readlane_b32 s76, v252, 20
	v_readlane_b32 s84, v252, 28
	v_readlane_b32 s85, v252, 29
	v_lshl_add_u32 v16, v30, 2, 0
	v_add_u32_e32 v32, 0xd800, v16
	v_lshl_add_u64 v[20:21], v[18:19], 2, s[84:85]
	global_load_dwordx4 v[18:21], v[20:21], off
	v_or_b32_e32 v134, 16, v22
	v_mad_i64_i32 v[140:141], s[0:1], v134, s55, v[28:29]
	v_lshl_add_u64 v[142:143], v[140:141], 0, v[26:27]
	global_load_dwordx2 v[144:145], v[142:143], off offset:2048
	v_or_b32_e32 v146, 32, v22
	v_mad_i64_i32 v[148:149], s[0:1], v146, s55, v[28:29]
	v_lshl_add_u64 v[150:151], v[148:149], 0, v[26:27]
	v_or_b32_e32 v152, 48, v22
	global_load_dwordx2 v[154:155], v[150:151], off offset:2048
	v_mad_i64_i32 v[156:157], s[0:1], v152, s55, v[28:29]
	v_lshl_add_u64 v[166:167], v[156:157], 0, v[26:27]
	global_load_dwordx2 v[168:169], v[166:167], off offset:2048
	v_add_u32_e32 v16, 0xdc00, v16
	ds_read2_b32 v[24:25], v32 offset1:16
	ds_read2_b32 v[50:51], v32 offset0:64 offset1:80
	ds_read2_b32 v[52:53], v32 offset0:128 offset1:144
	ds_read2_b32 v[54:55], v32 offset0:192 offset1:208
	ds_read2_b32 v[56:57], v16 offset1:16
	ds_read2_b32 v[58:59], v16 offset0:64 offset1:80
	ds_read2_b32 v[60:61], v16 offset0:128 offset1:144
	ds_read2_b32 v[62:63], v16 offset0:192 offset1:208
	ds_read2_b32 v[46:47], v32 offset0:32 offset1:48
	ds_read2_b32 v[44:45], v32 offset0:96 offset1:112
	ds_read2_b32 v[42:43], v32 offset0:160 offset1:176
	ds_read2_b32 v[40:41], v32 offset0:224 offset1:240
	ds_read2_b32 v[38:39], v16 offset0:32 offset1:48
	ds_read2_b32 v[36:37], v16 offset0:96 offset1:112
	ds_read2_b32 v[34:35], v16 offset0:160 offset1:176
	ds_read2_b32 v[32:33], v16 offset0:224 offset1:240
	s_waitcnt lgkmcnt(14)
	v_mov_b32_e32 v64, v25
	v_mov_b32_e32 v65, v24
	v_mov_b32_e32 v24, v51
	v_mov_b32_e32 v25, v50
	s_waitcnt lgkmcnt(13)
	v_mov_b32_e32 v50, v53
	v_mov_b32_e32 v51, v52
	s_waitcnt lgkmcnt(12)
	v_mov_b32_e32 v52, v55
	v_mov_b32_e32 v53, v54
	s_waitcnt lgkmcnt(11)
	v_mov_b32_e32 v54, v57
	v_mov_b32_e32 v55, v56
	s_waitcnt lgkmcnt(10)
	v_mov_b32_e32 v56, v59
	v_mov_b32_e32 v57, v58
	s_waitcnt lgkmcnt(9)
	v_mov_b32_e32 v58, v61
	v_mov_b32_e32 v59, v60
	s_waitcnt lgkmcnt(8)
	v_mov_b32_e32 v60, v63
	v_mov_b32_e32 v61, v62
	v_pk_add_f32 v[62:63], v[64:65], 0 op_sel_hi:[1,0]
	s_mov_b32 s0, 0x358637bd
	v_pk_add_f32 v[24:25], v[62:63], v[24:25]
	v_mov_b64_e32 v[30:31], s[0:1]
	v_pk_add_f32 v[24:25], v[24:25], v[50:51]
	v_mov_b32_e32 v23, s8
	v_pk_add_f32 v[24:25], v[24:25], v[52:53]
	s_brev_b32 s8, 60
	v_pk_add_f32 v[24:25], v[24:25], v[54:55]
	s_add_u32 s0, s61, s9
	v_pk_add_f32 v[24:25], v[24:25], v[56:57]
	v_readlane_b32 s1, v253, 31
	v_pk_add_f32 v[24:25], v[24:25], v[58:59]
	s_addc_u32 s1, s1, 0
	v_pk_add_f32 v[24:25], v[24:25], v[60:61]
	v_readlane_b32 s77, v252, 21
	v_pk_fma_f32 v[50:51], v[24:25], s[8:9], v[30:31] op_sel_hi:[1,0,0]
	v_lshl_add_u64 v[24:25], s[0:1], 0, v[26:27]
	v_mul_f32_e32 v16, 0x4b800000, v51
	v_cmp_gt_f32_e32 vcc, s33, v51
	v_readlane_b32 s78, v252, 22
	v_readlane_b32 s79, v252, 23
	v_cndmask_b32_e32 v16, v51, v16, vcc
	v_rsq_f32_e32 v16, v16
	v_readlane_b32 s80, v252, 24
	v_readlane_b32 s81, v252, 25
	v_readlane_b32 s82, v252, 26
	v_mul_f32_e32 v51, 0x45800000, v16
	v_cndmask_b32_e32 v16, v16, v51, vcc
	v_pk_mul_f32 v[12:13], v[12:13], v[16:17] op_sel_hi:[1,0]
	v_pk_mul_f32 v[14:15], v[14:15], v[16:17] op_sel_hi:[1,0]
	v_cmp_gt_f32_e32 vcc, s33, v50
	v_readlane_b32 s83, v252, 27
	v_readlane_b32 s86, v252, 30
	v_readlane_b32 s87, v252, 31
	v_readlane_b32 s88, v252, 32
	v_readlane_b32 s89, v252, 33
	v_readlane_b32 s90, v252, 34
	v_readlane_b32 s91, v252, 35
	s_waitcnt vmcnt(0)
; __device__ __forceinline__ unsigned pk2(float lo, float hi) { return pg8::cvt_pk_bf16(lo, hi); }
; __device__ __forceinline__ float siluf(float x) { return x * __builtin_amdgcn_rcpf(1.0f + __expf(-x)); }
; template <int TY> __device__ __forceinline__ void mc_item(const Params& p, ldsp lds, int item) {
;     ...
;     for (int ei = 0; ei < ET; ++ei) { const int e0 = 16 * (wave * ET + ei) + 4 * q4; const f32x4 w4 = *(const f32x4*)(nwp + e0);
; #pragma unroll
;         for (int tk = 0; tk < 4; ++tk) { const size_t row = (size_t)row0 + 16 * tk + l15;
;             const u32x2 gw = *(const u32x2*)(Pb + row * PP + goff + e0);
;             const float g0 = bf2f(gw.x & 0xffffu), g1 = bf2f(gw.x >> 16), g2 = bf2f(gw.y & 0xffffu), g3 = bf2f(gw.y >> 16);
;             const f32x4 v = acc[ei][tk] * rstd[tk] * w4;
;             float y0 = v[0] * siluf(g0), y1 = v[1] * siluf(g1), y2 = v[2] * siluf(g2), y3 = v[3] * siluf(g3);
;     ...
;             if (!(fabsf(y0) < 1e30f)) y0 = 0.f; if (!(fabsf(y1) < 1e30f)) y1 = 0.f; if (!(fabsf(y2) < 1e30f)) y2 = 0.f; if (!(fabsf(y3) < 1e30f)) y3 = 0.f;
;     ...
;             u32x2 o; o.x = pk2(y0, y1); o.y = pk2(y2, y3);
;             *(u32x2*)(Y + row * LDY + ycol + e0) = o; } }
	v_lshlrev_b32_e32 v16, 16, v48
	v_mul_f32_e32 v52, 0xbfb8aa3b, v16
	v_exp_f32_e32 v52, v52
	v_and_b32_e32 v48, 0xffff0000, v48
	v_lshlrev_b32_e32 v51, 16, v49
	v_and_b32_e32 v49, 0xffff0000, v49
	v_mul_f32_e32 v53, 0xbfb8aa3b, v48
	v_mul_f32_e32 v54, 0xbfb8aa3b, v51
	v_mul_f32_e32 v55, 0xbfb8aa3b, v49
	v_exp_f32_e32 v53, v53
	v_add_f32_e32 v52, 1.0, v52
	v_exp_f32_e32 v54, v54
	v_exp_f32_e32 v55, v55
	v_rcp_f32_e32 v52, v52
	v_add_f32_e32 v53, 1.0, v53
	v_pk_mul_f32 v[12:13], v[12:13], v[18:19]
	v_add_f32_e32 v54, 1.0, v54
	v_rcp_f32_e32 v53, v53
	v_add_f32_e32 v55, 1.0, v55
	v_mul_f32_e32 v16, v52, v16
	v_rcp_f32_e32 v54, v54
	v_mul_f32_e32 v12, v12, v16
	v_rcp_f32_e32 v16, v55
	v_mul_f32_e32 v48, v53, v48
	v_pk_mul_f32 v[14:15], v[14:15], v[20:21]
	v_mul_f32_e32 v13, v13, v48
	v_mul_f32_e32 v48, v54, v51
	v_mul_f32_e32 v16, v16, v49
	v_mul_f32_e32 v14, v14, v48
	v_mul_f32_e32 v15, v15, v16
	v_cvt_pk_bf16_f32 v12, v12, v13
	v_cvt_pk_bf16_f32 v13, v14, v15
	v_lshlrev_b64 v[14:15], 11, v[22:23]
	v_lshl_add_u64 v[14:15], v[24:25], 0, v[14:15]
	global_store_dwordx2 v[14:15], v[12:13], off nt
	v_or_b32_e32 v12, 16, v22
	v_mad_i64_i32 v[14:15], s[0:1], v12, s55, v[28:29]
	v_lshl_add_u64 v[14:15], v[14:15], 0, v[26:27]
	v_mul_f32_e32 v16, 0x4b800000, v50
	v_cndmask_b32_e32 v16, v50, v16, vcc
	v_rsq_f32_e32 v16, v16
	v_mov_b32_e32 v13, v23
	v_or_b32_e32 v48, 32, v22
	v_lshlrev_b64 v[12:13], 11, v[12:13]
	v_mul_f32_e32 v49, 0x45800000, v16
	v_cndmask_b32_e32 v16, v16, v49, vcc
	v_pk_mul_f32 v[8:9], v[8:9], v[16:17] op_sel_hi:[1,0]
	v_pk_mul_f32 v[10:11], v[10:11], v[16:17] op_sel_hi:[1,0]
	v_pk_mul_f32 v[8:9], v[8:9], v[18:19]
	v_mad_i64_i32 v[50:51], s[0:1], v48, s55, v[28:29]
	v_lshl_add_u64 v[12:13], v[24:25], 0, v[12:13]
	v_pk_mul_f32 v[10:11], v[10:11], v[20:21]
	v_lshl_add_u64 v[50:51], v[50:51], 0, v[26:27]
	v_or_b32_e32 v22, 48, v22
	v_lshlrev_b32_e32 v16, 16, v144
	v_and_b32_e32 v14, 0xffff0000, v144
	v_lshlrev_b32_e32 v49, 16, v145
	v_and_b32_e32 v15, 0xffff0000, v145
	v_mul_f32_e32 v52, 0xbfb8aa3b, v16
	v_mul_f32_e32 v53, 0xbfb8aa3b, v14
	v_mul_f32_e32 v54, 0xbfb8aa3b, v49
	v_mul_f32_e32 v55, 0xbfb8aa3b, v15
	v_exp_f32_e32 v52, v52
	v_exp_f32_e32 v53, v53
	v_exp_f32_e32 v54, v54
	v_exp_f32_e32 v55, v55
	v_add_f32_e32 v52, 1.0, v52
	v_add_f32_e32 v53, 1.0, v53
	v_add_f32_e32 v54, 1.0, v54
	v_add_f32_e32 v55, 1.0, v55
	v_rcp_f32_e32 v52, v52
	v_rcp_f32_e32 v53, v53
	v_rcp_f32_e32 v54, v54
	v_rcp_f32_e32 v55, v55
	v_mul_f32_e32 v16, v52, v16
	v_mul_f32_e32 v14, v53, v14
	v_mul_f32_e32 v49, v54, v49
	v_mul_f32_e32 v15, v55, v15
	v_mul_f32_e32 v8, v8, v16
	v_mul_f32_e32 v9, v9, v14
	v_mul_f32_e32 v10, v10, v49
	v_mul_f32_e32 v11, v11, v15
	v_cvt_pk_bf16_f32 v8, v8, v9
	v_cvt_pk_bf16_f32 v9, v10, v11
	global_store_dwordx2 v[12:13], v[8:9], off nt
	s_waitcnt lgkmcnt(7)
	v_mov_b32_e32 v12, v47
	v_mov_b32_e32 v13, v46
	s_waitcnt lgkmcnt(6)
	v_mov_b32_e32 v14, v45
	v_mov_b32_e32 v15, v44
	v_pk_add_f32 v[12:13], v[12:13], 0 op_sel_hi:[1,0]
	s_waitcnt lgkmcnt(5)
	v_mov_b32_e32 v44, v43
	v_mov_b32_e32 v45, v42
	v_pk_add_f32 v[12:13], v[12:13], v[14:15]
	s_waitcnt lgkmcnt(4)
	v_mov_b32_e32 v42, v41
	v_mov_b32_e32 v43, v40
	v_pk_add_f32 v[12:13], v[12:13], v[44:45]
	s_waitcnt lgkmcnt(3)
	v_mov_b32_e32 v40, v39
	v_mov_b32_e32 v41, v38
	v_pk_add_f32 v[12:13], v[12:13], v[42:43]
	s_waitcnt lgkmcnt(2)
	v_mov_b32_e32 v38, v37
	v_mov_b32_e32 v39, v36
	v_pk_add_f32 v[12:13], v[12:13], v[40:41]
	s_waitcnt lgkmcnt(1)
	v_mov_b32_e32 v36, v35
	v_mov_b32_e32 v37, v34
	v_pk_add_f32 v[12:13], v[12:13], v[38:39]
	s_waitcnt lgkmcnt(0)
	v_mov_b32_e32 v34, v33
	v_mov_b32_e32 v35, v32
	v_pk_add_f32 v[12:13], v[12:13], v[36:37]
	v_mov_b32_e32 v49, v23
	v_pk_add_f32 v[12:13], v[12:13], v[34:35]
	v_lshlrev_b64 v[10:11], 11, v[48:49]
	v_pk_fma_f32 v[12:13], v[12:13], s[8:9], v[30:31] op_sel_hi:[1,0,0]
	v_lshl_add_u64 v[10:11], v[24:25], 0, v[10:11]
	v_mul_f32_e32 v14, 0x4b800000, v13
	v_cmp_gt_f32_e32 vcc, s33, v13
	s_nop 1
	v_cndmask_b32_e32 v13, v13, v14, vcc
	v_rsq_f32_e32 v13, v13
	v_mad_i64_i32 v[14:15], s[0:1], v22, s55, v[28:29]
	v_lshl_add_u64 v[14:15], v[14:15], 0, v[26:27]
	v_mul_f32_e32 v16, 0x45800000, v13
	v_cndmask_b32_e32 v16, v13, v16, vcc
	v_pk_mul_f32 v[4:5], v[4:5], v[16:17] op_sel_hi:[1,0]
	v_pk_mul_f32 v[6:7], v[6:7], v[16:17] op_sel_hi:[1,0]
	v_pk_mul_f32 v[4:5], v[18:19], v[4:5]
	v_pk_mul_f32 v[6:7], v[20:21], v[6:7]
	v_cmp_gt_f32_e32 vcc, s33, v12
	v_lshlrev_b32_e32 v13, 16, v154
	v_and_b32_e32 v8, 0xffff0000, v154
	v_lshlrev_b32_e32 v16, 16, v155
	v_and_b32_e32 v9, 0xffff0000, v155
	v_mul_f32_e32 v26, 0xbfb8aa3b, v13
	v_mul_f32_e32 v27, 0xbfb8aa3b, v8
	v_mul_f32_e32 v28, 0xbfb8aa3b, v16
	v_mul_f32_e32 v29, 0xbfb8aa3b, v9
	v_exp_f32_e32 v26, v26
	v_exp_f32_e32 v27, v27
	v_exp_f32_e32 v28, v28
	v_exp_f32_e32 v29, v29
	v_add_f32_e32 v26, 1.0, v26
	v_add_f32_e32 v27, 1.0, v27
	v_add_f32_e32 v28, 1.0, v28
	v_add_f32_e32 v29, 1.0, v29
	v_rcp_f32_e32 v26, v26
	v_rcp_f32_e32 v27, v27
	v_rcp_f32_e32 v28, v28
	v_rcp_f32_e32 v29, v29
	v_mul_f32_e32 v13, v26, v13
	v_mul_f32_e32 v8, v27, v8
	v_mul_f32_e32 v16, v28, v16
	v_mul_f32_e32 v9, v29, v9
	v_mul_f32_e32 v4, v4, v13
	v_mul_f32_e32 v5, v5, v8
	v_mul_f32_e32 v6, v6, v16
	v_mul_f32_e32 v7, v7, v9
	v_cvt_pk_bf16_f32 v4, v4, v5
	v_cvt_pk_bf16_f32 v5, v6, v7
	global_store_dwordx2 v[10:11], v[4:5], off nt
	v_mul_f32_e32 v6, 0x4b800000, v12
	v_cndmask_b32_e32 v6, v12, v6, vcc
	v_rsq_f32_e32 v8, v6
	v_lshlrev_b64 v[6:7], 11, v[22:23]
	v_mul_f32_e32 v9, 0x45800000, v8
	v_cndmask_b32_e32 v8, v8, v9, vcc
	v_pk_mul_f32 v[0:1], v[0:1], v[8:9] op_sel_hi:[1,0]
	v_pk_mul_f32 v[2:3], v[2:3], v[8:9] op_sel_hi:[1,0]
	v_pk_mul_f32 v[0:1], v[18:19], v[0:1]
	v_pk_mul_f32 v[2:3], v[20:21], v[2:3]
	v_lshlrev_b32_e32 v8, 16, v168
	v_and_b32_e32 v4, 0xffff0000, v168
	v_lshlrev_b32_e32 v9, 16, v169
	v_and_b32_e32 v5, 0xffff0000, v169
	v_mul_f32_e32 v10, 0xbfb8aa3b, v8
	v_mul_f32_e32 v11, 0xbfb8aa3b, v4
	v_mul_f32_e32 v12, 0xbfb8aa3b, v9
	v_mul_f32_e32 v13, 0xbfb8aa3b, v5
	v_exp_f32_e32 v10, v10
	v_exp_f32_e32 v11, v11
	v_exp_f32_e32 v12, v12
	v_exp_f32_e32 v13, v13
	v_add_f32_e32 v10, 1.0, v10
	v_add_f32_e32 v11, 1.0, v11
	v_add_f32_e32 v12, 1.0, v12
	v_add_f32_e32 v13, 1.0, v13
	v_rcp_f32_e32 v10, v10
	v_rcp_f32_e32 v11, v11
	v_rcp_f32_e32 v12, v12
	v_rcp_f32_e32 v13, v13
	v_mul_f32_e32 v8, v10, v8
	v_mul_f32_e32 v4, v11, v4
	v_mul_f32_e32 v9, v12, v9
	v_mul_f32_e32 v5, v13, v5
	v_mul_f32_e32 v0, v0, v8
	v_mul_f32_e32 v1, v1, v4
	v_mul_f32_e32 v2, v2, v9
	v_mul_f32_e32 v3, v3, v5
	v_cvt_pk_bf16_f32 v0, v0, v1
	v_cvt_pk_bf16_f32 v1, v2, v3
	v_lshl_add_u64 v[2:3], v[24:25], 0, v[6:7]
	global_store_dwordx2 v[2:3], v[0:1], off nt
	s_waitcnt vmcnt(0) lgkmcnt(0)
	s_barrier

; #define BSYNC() do { asm volatile("s_waitcnt vmcnt(0) lgkmcnt(0)" ::: "memory"); __syncthreads(); } while (0)
; template <int TY> __device__ __forceinline__ void mc_item(const Params& p, ldsp lds, int item) {
;     ...
;     BSYNC();
; #pragma unroll
;     for (int tk = 0; tk < 4; ++tk) { float s = 0.f;
; #pragma unroll
;         for (int w = 0; w < 8; ++w) s += RED[w * 64 + 16 * tk + l15];
;         rstd[tk] = rsqrtf(s * (1.0f / DV) + EPS); }
;     const float* nwp = TY == 0 ? p.in[12] : (TY == 1 ? p.in[14] : p.in[17]);
;     const int goff = TY == 0 ? E_RA + h * 128 : (TY == 1 ? E_GB + h * 128 : O_G + h * 512);
;     constexpr int LDY = TY == 2 ? 2048 : 1024; const int ycol = TY == 0 ? h * 128 : (TY == 1 ? 512 + h * 128 : h * 512);
;     bf16_t* Y = (bf16_t*)(p.ws + WS_Y);
; #pragma unroll
;     for (int ei = 0; ei < ET; ++ei) { const int e0 = 16 * (wave * ET + ei) + 4 * q4; const f32x4 w4 = *(const f32x4*)(nwp + e0);
; #pragma unroll
;         for (int tk = 0; tk < 4; ++tk) { const size_t row = (size_t)row0 + 16 * tk + l15;
;             const u32x2 gw = *(const u32x2*)(Pb + row * PP + goff + e0);
.LBB0_1254:
	s_or_b64 exec, exec, s[0:1]
	v_lshl_add_u32 v8, v24, 2, 0
	v_add_u32_e32 v16, 0x13800, v8
	v_or_b32_e32 v22, s17, v24
	s_waitcnt vmcnt(0) lgkmcnt(0)
	s_waitcnt lgkmcnt(0)
	s_barrier
	ds_read2_b32 v[8:9], v16 offset1:16
	ds_read2_b32 v[10:11], v16 offset0:64 offset1:80
	ds_read2_b32 v[24:25], v16 offset0:128 offset1:144
	ds_read2_b32 v[26:27], v16 offset0:192 offset1:208
	v_add_u32_e32 v40, 0x400, v16
	s_waitcnt lgkmcnt(3)
	v_mov_b32_e32 v36, v9
	v_mov_b32_e32 v37, v8
	v_pk_add_f32 v[8:9], v[36:37], 0 op_sel_hi:[1,0]
	s_waitcnt lgkmcnt(2)
	v_mov_b32_e32 v36, v11
	v_mov_b32_e32 v37, v10
	ds_read2_b32 v[28:29], v40 offset1:16
	ds_read2_b32 v[30:31], v40 offset0:64 offset1:80
	ds_read2_b32 v[32:33], v40 offset0:128 offset1:144
	ds_read2_b32 v[34:35], v40 offset0:192 offset1:208
	v_pk_add_f32 v[8:9], v[8:9], v[36:37]
	s_waitcnt lgkmcnt(5)
	v_mov_b32_e32 v10, v25
	v_mov_b32_e32 v11, v24
	v_pk_add_f32 v[8:9], v[8:9], v[10:11]
	s_waitcnt lgkmcnt(4)
	v_mov_b32_e32 v10, v27
	v_mov_b32_e32 v11, v26
	v_pk_add_f32 v[8:9], v[8:9], v[10:11]
	s_waitcnt lgkmcnt(3)
	v_mov_b32_e32 v10, v29
	v_mov_b32_e32 v11, v28
	v_pk_add_f32 v[8:9], v[8:9], v[10:11]
	s_waitcnt lgkmcnt(2)
	v_mov_b32_e32 v10, v31
	v_mov_b32_e32 v11, v30
	v_pk_add_f32 v[8:9], v[8:9], v[10:11]
	s_waitcnt lgkmcnt(1)
	v_mov_b32_e32 v10, v33
	v_mov_b32_e32 v11, v32
	v_pk_add_f32 v[8:9], v[8:9], v[10:11]
	s_waitcnt lgkmcnt(0)
	v_mov_b32_e32 v10, v35
	v_mov_b32_e32 v11, v34
	s_mov_b32 s0, 0x358637bd
	v_pk_add_f32 v[8:9], v[8:9], v[10:11]
	v_mov_b64_e32 v[10:11], s[0:1]
	s_brev_b32 s18, 60
	v_pk_fma_f32 v[8:9], v[8:9], s[18:19], v[10:11] op_sel_hi:[1,0,0]
	v_readlane_b32 s76, v252, 20
	v_mul_f32_e32 v24, 0x4b800000, v9
	v_cmp_gt_f32_e64 s[0:1], s33, v9
	v_cmp_gt_f32_e32 vcc, s33, v8
	v_readlane_b32 s88, v252, 32
	v_cndmask_b32_e64 v9, v9, v24, s[0:1]
	v_rsq_f32_e32 v9, v9
	v_readlane_b32 s89, v252, 33
	v_readlane_b32 s77, v252, 21
	v_readlane_b32 s78, v252, 22
	v_mul_f32_e32 v24, 0x45800000, v9
	v_cndmask_b32_e64 v32, v9, v24, s[0:1]
	v_mul_f32_e32 v9, 0x4b800000, v8
	v_cndmask_b32_e32 v8, v8, v9, vcc
	v_rsq_f32_e32 v8, v8
	v_readlane_b32 s79, v252, 23
	v_readlane_b32 s80, v252, 24
	v_readlane_b32 s81, v252, 25
	v_mul_f32_e32 v9, 0x45800000, v8
	v_cndmask_b32_e32 v30, v8, v9, vcc
	ds_read2_b32 v[8:9], v16 offset0:32 offset1:48
	ds_read2_b32 v[24:25], v16 offset0:96 offset1:112
	ds_read2_b32 v[26:27], v16 offset0:160 offset1:176
	ds_read2_b32 v[28:29], v16 offset0:224 offset1:240
	ds_read2_b32 v[34:35], v40 offset0:32 offset1:48
	ds_read2_b32 v[36:37], v40 offset0:96 offset1:112
	ds_read2_b32 v[38:39], v40 offset0:160 offset1:176
	ds_read2_b32 v[40:41], v40 offset0:224 offset1:240
	s_waitcnt lgkmcnt(7)
	v_mov_b32_e32 v42, v9
	v_mov_b32_e32 v43, v8
	v_pk_add_f32 v[8:9], v[42:43], 0 op_sel_hi:[1,0]
	s_waitcnt lgkmcnt(6)
	v_mov_b32_e32 v42, v25
	v_mov_b32_e32 v43, v24
	v_pk_add_f32 v[8:9], v[8:9], v[42:43]
	s_waitcnt lgkmcnt(5)
	v_mov_b32_e32 v24, v27
	v_mov_b32_e32 v25, v26
	v_pk_add_f32 v[8:9], v[8:9], v[24:25]
	s_waitcnt lgkmcnt(4)
	v_mov_b32_e32 v24, v29
	v_mov_b32_e32 v25, v28
	v_pk_add_f32 v[8:9], v[8:9], v[24:25]
	s_waitcnt lgkmcnt(3)
	v_mov_b32_e32 v24, v35
	v_mov_b32_e32 v25, v34
	v_pk_add_f32 v[8:9], v[8:9], v[24:25]
	s_waitcnt lgkmcnt(2)
	v_mov_b32_e32 v24, v37
	v_mov_b32_e32 v25, v36
	v_pk_add_f32 v[8:9], v[8:9], v[24:25]
	s_waitcnt lgkmcnt(1)
	v_mov_b32_e32 v24, v39
	v_mov_b32_e32 v25, v38
	v_pk_add_f32 v[8:9], v[8:9], v[24:25]
	s_waitcnt lgkmcnt(0)
	v_mov_b32_e32 v24, v41
	v_mov_b32_e32 v25, v40
	v_pk_add_f32 v[8:9], v[8:9], v[24:25]
	v_or_b32_e32 v24, s13, v23
	v_pk_fma_f32 v[8:9], v[8:9], s[18:19], v[10:11] op_sel_hi:[1,0,0]
	s_add_u32 s18, s26, s16
	v_mul_f32_e32 v10, 0x4b800000, v9
	v_cmp_gt_f32_e64 s[0:1], s33, v9
	v_cmp_gt_f32_e32 vcc, s33, v8
	s_addc_u32 s19, s27, 0
	v_cndmask_b32_e64 v9, v9, v10, s[0:1]
	v_rsq_f32_e32 v9, v9
	v_ashrrev_i32_e32 v25, 31, v24
	v_mov_b64_e32 v[28:29], s[18:19]
	v_mov_b32_e32 v23, s9
	v_mul_f32_e32 v10, 0x45800000, v9
	v_cndmask_b32_e64 v26, v9, v10, s[0:1]
	v_mul_f32_e32 v9, 0x4b800000, v8
	v_cndmask_b32_e32 v8, v8, v9, vcc
	v_rsq_f32_e32 v8, v8
	s_add_u32 s0, s68, s16
	v_mad_i64_i32 v[34:35], s[16:17], v22, s55, v[28:29]
	v_mul_f32_e32 v9, 0x45800000, v8
	v_cndmask_b32_e32 v16, v8, v9, vcc
	v_lshl_add_u64 v[8:9], v[24:25], 2, s[88:89]
	v_lshlrev_b64 v[24:25], 1, v[24:25]
	v_lshl_add_u64 v[34:35], v[34:35], 0, v[24:25]
	v_add_co_u32_e32 v34, vcc, s57, v34
	global_load_dwordx4 v[8:11], v[8:9], off
	s_nop 0
	v_addc_co_u32_e32 v35, vcc, 0, v35, vcc
	global_load_dwordx2 v[34:35], v[34:35], off offset:2048
	s_mov_b32 s98, s57
	s_mov_b32 s99, 0
	v_or_b32_e32 v64, 16, v22
	v_mad_i64_i32 v[134:135], s[16:17], v64, s55, v[28:29]
	v_lshl_add_u64 v[140:141], v[134:135], 0, v[24:25]
	v_lshl_add_u64 v[142:143], v[140:141], 0, s[98:99]
	global_load_dwordx2 v[144:145], v[142:143], off offset:2048
	v_or_b32_e32 v146, 32, v22
	v_mad_i64_i32 v[148:149], s[16:17], v146, s55, v[28:29]
	v_lshl_add_u64 v[150:151], v[148:149], 0, v[24:25]
	v_lshl_add_u64 v[152:153], v[150:151], 0, s[98:99]
	global_load_dwordx2 v[154:155], v[152:153], off offset:2048
	v_or_b32_e32 v156, 48, v22
	v_mad_i64_i32 v[166:167], s[16:17], v156, s55, v[28:29]
	v_lshl_add_u64 v[168:169], v[166:167], 0, v[24:25]
	v_lshl_add_u64 v[172:173], v[168:169], 0, s[98:99]
	global_load_dwordx2 v[174:175], v[172:173], off offset:2048
	s_addc_u32 s1, s69, 0
	s_mov_b32 s9, 0x1ec21000
	v_pk_mul_f32 v[0:1], v[0:1], v[16:17] op_sel_hi:[1,0]
	v_pk_mul_f32 v[2:3], v[2:3], v[16:17] op_sel_hi:[1,0]
	v_readlane_b32 s82, v252, 26
	v_readlane_b32 s83, v252, 27
	v_readlane_b32 s84, v252, 28
	v_readlane_b32 s85, v252, 29
	v_readlane_b32 s86, v252, 30
	v_readlane_b32 s87, v252, 31
	v_readlane_b32 s90, v252, 34
	v_readlane_b32 s91, v252, 35
	s_waitcnt vmcnt(0)
; __device__ __forceinline__ unsigned pk2(float lo, float hi) { return pg8::cvt_pk_bf16(lo, hi); }
; __device__ __forceinline__ float siluf(float x) { return x * __builtin_amdgcn_rcpf(1.0f + __expf(-x)); }
; template <int TY> __device__ __forceinline__ void mc_item(const Params& p, ldsp lds, int item) {
;     ...
;     for (int ei = 0; ei < ET; ++ei) { const int e0 = 16 * (wave * ET + ei) + 4 * q4; const f32x4 w4 = *(const f32x4*)(nwp + e0);
; #pragma unroll
;         for (int tk = 0; tk < 4; ++tk) { const size_t row = (size_t)row0 + 16 * tk + l15;
;             const u32x2 gw = *(const u32x2*)(Pb + row * PP + goff + e0);
;             const float g0 = bf2f(gw.x & 0xffffu), g1 = bf2f(gw.x >> 16), g2 = bf2f(gw.y & 0xffffu), g3 = bf2f(gw.y >> 16);
;             const f32x4 v = acc[ei][tk] * rstd[tk] * w4;
;             float y0 = v[0] * siluf(g0), y1 = v[1] * siluf(g1), y2 = v[2] * siluf(g2), y3 = v[3] * siluf(g3);
;     ...
;             if (!(fabsf(y0) < 1e30f)) y0 = 0.f; if (!(fabsf(y1) < 1e30f)) y1 = 0.f; if (!(fabsf(y2) < 1e30f)) y2 = 0.f; if (!(fabsf(y3) < 1e30f)) y3 = 0.f;
;     ...
;             u32x2 o; o.x = pk2(y0, y1); o.y = pk2(y2, y3);
;             *(u32x2*)(Y + row * LDY + ycol + e0) = o; } }
	v_pk_mul_f32 v[0:1], v[8:9], v[0:1]
	v_pk_mul_f32 v[2:3], v[10:11], v[2:3]
	v_lshlrev_b32_e32 v27, 16, v34
	v_lshlrev_b32_e32 v33, 16, v35
	v_pk_mul_f32 v[18:19], v[18:19], v[32:33] op_sel_hi:[1,0]
	v_pk_mul_f32 v[20:21], v[20:21], v[32:33] op_sel_hi:[1,0]
	v_mul_f32_e32 v32, 0xbfb8aa3b, v27
	v_exp_f32_e32 v32, v32
	v_and_b32_e32 v31, 0xffff0000, v34
	v_pk_mul_f32 v[18:19], v[18:19], v[8:9]
	v_and_b32_e32 v34, 0xffff0000, v35
	v_add_f32_e32 v32, 1.0, v32
	v_rcp_f32_e32 v32, v32
	v_pk_mul_f32 v[20:21], v[20:21], v[10:11]
	v_mul_f32_e32 v27, v32, v27
	v_mul_f32_e32 v18, v18, v27
	v_mul_f32_e32 v27, 0xbfb8aa3b, v31
	v_exp_f32_e32 v27, v27
	s_nop 0
	v_add_f32_e32 v27, 1.0, v27
	v_rcp_f32_e32 v27, v27
	s_nop 0
	v_mul_f32_e32 v27, v27, v31
	v_mul_f32_e32 v19, v19, v27
	v_mul_f32_e32 v27, 0xbfb8aa3b, v33
	v_exp_f32_e32 v27, v27
	v_cvt_pk_bf16_f32 v18, v18, v19
	s_nop 0
	v_add_f32_e32 v27, 1.0, v27
	v_rcp_f32_e32 v27, v27
	s_nop 0
	v_mul_f32_e32 v27, v27, v33
	v_mul_f32_e32 v20, v20, v27
	v_mul_f32_e32 v27, 0xbfb8aa3b, v34
	v_exp_f32_e32 v27, v27
	s_nop 0
	v_add_f32_e32 v27, 1.0, v27
	v_rcp_f32_e32 v27, v27
	s_nop 0
	v_mul_f32_e32 v27, v27, v34
	v_mul_f32_e32 v21, v21, v27
	v_cvt_pk_bf16_f32 v19, v20, v21
	v_lshlrev_b64 v[20:21], 11, v[22:23]
	v_lshl_add_u64 v[20:21], s[0:1], 0, v[20:21]
	v_lshl_add_u64 v[20:21], v[20:21], 0, v[24:25]
	v_add_co_u32_e32 v20, vcc, s9, v20
	s_nop 1
	v_addc_co_u32_e32 v21, vcc, 0, v21, vcc
	global_store_dwordx2 v[20:21], v[18:19], off offset:1024 nt
	v_or_b32_e32 v18, 16, v22
	v_mad_i64_i32 v[20:21], s[16:17], v18, s55, v[28:29]
	v_lshl_add_u64 v[20:21], v[20:21], 0, v[24:25]
	s_nop 0
	v_mov_b32_e32 v19, v23
	s_nop 0
	v_lshl_add_u64 v[20:21], v[20:21], 0, s[98:99]
	v_lshlrev_b32_e32 v27, 16, v144
	v_lshlrev_b32_e32 v31, 16, v145
	v_pk_mul_f32 v[12:13], v[12:13], v[30:31] op_sel_hi:[1,0]
	v_pk_mul_f32 v[14:15], v[14:15], v[30:31] op_sel_hi:[1,0]
	v_mul_f32_e32 v30, 0xbfb8aa3b, v27
	v_exp_f32_e32 v30, v30
	v_and_b32_e32 v20, 0xffff0000, v144
	v_pk_mul_f32 v[12:13], v[12:13], v[8:9]
	v_and_b32_e32 v21, 0xffff0000, v145
	v_add_f32_e32 v30, 1.0, v30
	v_rcp_f32_e32 v30, v30
	v_pk_mul_f32 v[14:15], v[14:15], v[10:11]
	v_mul_f32_e32 v27, v30, v27
	v_mul_f32_e32 v12, v12, v27
	v_mul_f32_e32 v27, 0xbfb8aa3b, v20
	v_exp_f32_e32 v27, v27
	s_nop 0
	v_add_f32_e32 v27, 1.0, v27
	v_rcp_f32_e32 v27, v27
	s_nop 0
	v_mul_f32_e32 v20, v27, v20
	v_mul_f32_e32 v13, v13, v20
	v_mul_f32_e32 v20, 0xbfb8aa3b, v31
	v_exp_f32_e32 v20, v20
	v_cvt_pk_bf16_f32 v12, v12, v13
	v_pk_mul_f32 v[4:5], v[4:5], v[26:27] op_sel_hi:[1,0]
	v_pk_mul_f32 v[6:7], v[6:7], v[26:27] op_sel_hi:[1,0]
	v_add_f32_e32 v20, 1.0, v20
	v_rcp_f32_e32 v20, v20
	v_pk_mul_f32 v[4:5], v[8:9], v[4:5]
	v_pk_mul_f32 v[6:7], v[10:11], v[6:7]
	v_mul_f32_e32 v20, v20, v31
	v_mul_f32_e32 v14, v14, v20
	v_mul_f32_e32 v20, 0xbfb8aa3b, v21
	v_exp_f32_e32 v20, v20
	s_nop 0
	v_add_f32_e32 v20, 1.0, v20
	v_rcp_f32_e32 v20, v20
	s_nop 0
	v_mul_f32_e32 v20, v20, v21
	v_mul_f32_e32 v15, v15, v20
	v_cvt_pk_bf16_f32 v13, v14, v15
	v_lshlrev_b64 v[14:15], 11, v[18:19]
	v_lshl_add_u64 v[14:15], s[0:1], 0, v[14:15]
	v_lshl_add_u64 v[14:15], v[14:15], 0, v[24:25]
	v_add_co_u32_e32 v14, vcc, s9, v14
	s_nop 1
	v_addc_co_u32_e32 v15, vcc, 0, v15, vcc
	global_store_dwordx2 v[14:15], v[12:13], off offset:1024 nt
	v_or_b32_e32 v12, 32, v22
	v_mad_i64_i32 v[14:15], s[16:17], v12, s55, v[28:29]
	v_lshl_add_u64 v[14:15], v[14:15], 0, v[24:25]
	s_nop 0
	v_mov_b32_e32 v13, v23
	s_nop 0
	v_lshl_add_u64 v[14:15], v[14:15], 0, s[98:99]
	v_or_b32_e32 v22, 48, v22
	v_lshlrev_b32_e32 v18, 16, v154
	v_mul_f32_e32 v20, 0xbfb8aa3b, v18
	v_exp_f32_e32 v20, v20
	v_and_b32_e32 v14, 0xffff0000, v154
	v_lshlrev_b32_e32 v19, 16, v155
	v_and_b32_e32 v15, 0xffff0000, v155
	v_add_f32_e32 v20, 1.0, v20
	v_rcp_f32_e32 v20, v20
	s_nop 0
	v_mul_f32_e32 v18, v20, v18
	v_mul_f32_e32 v4, v4, v18
	v_mul_f32_e32 v18, 0xbfb8aa3b, v14
	v_exp_f32_e32 v18, v18
	s_nop 0
	v_add_f32_e32 v18, 1.0, v18
	v_rcp_f32_e32 v18, v18
	s_nop 0
	v_mul_f32_e32 v14, v18, v14
	v_mul_f32_e32 v5, v5, v14
	v_mul_f32_e32 v14, 0xbfb8aa3b, v19
	v_exp_f32_e32 v14, v14
	v_cvt_pk_bf16_f32 v4, v4, v5
	s_nop 0
	v_add_f32_e32 v14, 1.0, v14
	v_rcp_f32_e32 v14, v14
	s_nop 0
	v_mul_f32_e32 v14, v14, v19
	v_mul_f32_e32 v6, v6, v14
	v_mul_f32_e32 v14, 0xbfb8aa3b, v15
	v_exp_f32_e32 v14, v14
	s_nop 0
	v_add_f32_e32 v14, 1.0, v14
	v_rcp_f32_e32 v14, v14
	s_nop 0
	v_mul_f32_e32 v14, v14, v15
	v_mul_f32_e32 v7, v7, v14
	v_cvt_pk_bf16_f32 v5, v6, v7
	v_lshlrev_b64 v[6:7], 11, v[12:13]
	v_lshl_add_u64 v[6:7], s[0:1], 0, v[6:7]
	v_lshl_add_u64 v[6:7], v[6:7], 0, v[24:25]
	v_add_co_u32_e32 v6, vcc, s9, v6
	s_nop 1
	v_addc_co_u32_e32 v7, vcc, 0, v7, vcc
	global_store_dwordx2 v[6:7], v[4:5], off offset:1024 nt
	v_mad_i64_i32 v[4:5], s[16:17], v22, s55, v[28:29]
	v_lshl_add_u64 v[4:5], v[4:5], 0, v[24:25]
	s_nop 0
	s_nop 1
	v_lshl_add_u64 v[4:5], v[4:5], 0, s[98:99]
	v_lshlrev_b32_e32 v6, 16, v174
	v_mul_f32_e32 v8, 0xbfb8aa3b, v6
	v_exp_f32_e32 v8, v8
	v_and_b32_e32 v4, 0xffff0000, v174
	v_lshlrev_b32_e32 v7, 16, v175
	v_and_b32_e32 v5, 0xffff0000, v175
	v_add_f32_e32 v8, 1.0, v8
	v_rcp_f32_e32 v8, v8
	s_nop 0
	v_mul_f32_e32 v6, v8, v6
	v_mul_f32_e32 v0, v0, v6
	v_mul_f32_e32 v6, 0xbfb8aa3b, v4
	v_exp_f32_e32 v6, v6
	s_nop 0
	v_add_f32_e32 v6, 1.0, v6
	v_rcp_f32_e32 v6, v6
	s_nop 0
	v_mul_f32_e32 v4, v6, v4
	v_mul_f32_e32 v1, v1, v4
	v_mul_f32_e32 v4, 0xbfb8aa3b, v7
	v_exp_f32_e32 v4, v4
	v_cvt_pk_bf16_f32 v0, v0, v1
	s_nop 0
	v_add_f32_e32 v4, 1.0, v4
	v_rcp_f32_e32 v4, v4
	s_nop 0
	v_mul_f32_e32 v4, v4, v7
	v_mul_f32_e32 v2, v2, v4
	v_mul_f32_e32 v4, 0xbfb8aa3b, v5
	v_exp_f32_e32 v4, v4
	s_nop 0
	v_add_f32_e32 v4, 1.0, v4
	v_rcp_f32_e32 v4, v4
	s_nop 0
	v_mul_f32_e32 v4, v4, v5
	v_mul_f32_e32 v3, v3, v4
	v_cvt_pk_bf16_f32 v1, v2, v3
	v_lshlrev_b64 v[2:3], 11, v[22:23]
	v_lshl_add_u64 v[2:3], s[0:1], 0, v[2:3]
	v_lshl_add_u64 v[2:3], v[2:3], 0, v[24:25]
	v_add_co_u32_e32 v2, vcc, 0x1ec21000, v2
	s_nop 1
	v_addc_co_u32_e32 v3, vcc, 0, v3, vcc
	global_store_dwordx2 v[2:3], v[0:1], off offset:1024 nt
	s_waitcnt vmcnt(0) lgkmcnt(0)
	s_barrier
	s_branch .LBB0_1240

; #define BSYNC() do { asm volatile("s_waitcnt vmcnt(0) lgkmcnt(0)" ::: "memory"); __syncthreads(); } while (0)
; template <int TY> __device__ __forceinline__ void mc_item(const Params& p, ldsp lds, int item) {
;     ...
;     BSYNC();
; #pragma unroll
;     for (int tk = 0; tk < 4; ++tk) { float s = 0.f;
; #pragma unroll
;         for (int w = 0; w < 8; ++w) s += RED[w * 64 + 16 * tk + l15];
;         rstd[tk] = rsqrtf(s * (1.0f / DV) + EPS); }
;     const float* nwp = TY == 0 ? p.in[12] : (TY == 1 ? p.in[14] : p.in[17]);
;     const int goff = TY == 0 ? E_RA + h * 128 : (TY == 1 ? E_GB + h * 128 : O_G + h * 512);
;     constexpr int LDY = TY == 2 ? 2048 : 1024; const int ycol = TY == 0 ? h * 128 : (TY == 1 ? 512 + h * 128 : h * 512);
;     bf16_t* Y = (bf16_t*)(p.ws + WS_Y);
; #pragma unroll
;     for (int ei = 0; ei < ET; ++ei) { const int e0 = 16 * (wave * ET + ei) + 4 * q4; const f32x4 w4 = *(const f32x4*)(nwp + e0);
; #pragma unroll
;         for (int tk = 0; tk < 4; ++tk) { const size_t row = (size_t)row0 + 16 * tk + l15;
;             const u32x2 gw = *(const u32x2*)(Pb + row * PP + goff + e0);
.LBB0_1266:
	s_or_b64 exec, exec, s[0:1]
	s_lshl_b32 s9, s9, 1
	s_add_u32 s0, s26, s9
	v_or_b32_e32 v18, s10, v28
	s_addc_u32 s1, s27, 0
	v_or_b32_e32 v22, s11, v30
	s_waitcnt lgkmcnt(0)
	v_ashrrev_i32_e32 v19, 31, v18
	v_mov_b64_e32 v[28:29], s[0:1]
	v_lshlrev_b64 v[26:27], 1, v[18:19]
	v_mad_i64_i32 v[24:25], s[0:1], v22, s55, v[28:29]
	v_lshl_add_u64 v[24:25], v[24:25], 0, v[26:27]
	s_waitcnt vmcnt(0) lgkmcnt(0)
	s_barrier
	global_load_dwordx2 v[48:49], v[24:25], off offset:2048
	v_readlane_b32 s76, v252, 20
	v_readlane_b32 s84, v252, 28
	v_readlane_b32 s85, v252, 29
	v_lshl_add_u32 v16, v30, 2, 0
	v_add_u32_e32 v32, 0xd800, v16
	v_lshl_add_u64 v[20:21], v[18:19], 2, s[84:85]
	global_load_dwordx4 v[18:21], v[20:21], off
	v_or_b32_e32 v134, 16, v22
	v_mad_i64_i32 v[140:141], s[0:1], v134, s55, v[28:29]
	v_lshl_add_u64 v[142:143], v[140:141], 0, v[26:27]
	global_load_dwordx2 v[144:145], v[142:143], off offset:2048
	v_or_b32_e32 v146, 32, v22
	v_mad_i64_i32 v[148:149], s[0:1], v146, s55, v[28:29]
	v_lshl_add_u64 v[150:151], v[148:149], 0, v[26:27]
	v_or_b32_e32 v152, 48, v22
	global_load_dwordx2 v[154:155], v[150:151], off offset:2048
	v_mad_i64_i32 v[156:157], s[0:1], v152, s55, v[28:29]
	v_lshl_add_u64 v[166:167], v[156:157], 0, v[26:27]
	global_load_dwordx2 v[168:169], v[166:167], off offset:2048
	v_add_u32_e32 v16, 0xdc00, v16
	ds_read2_b32 v[24:25], v32 offset1:16
	ds_read2_b32 v[50:51], v32 offset0:64 offset1:80
	ds_read2_b32 v[52:53], v32 offset0:128 offset1:144
	ds_read2_b32 v[54:55], v32 offset0:192 offset1:208
	ds_read2_b32 v[56:57], v16 offset1:16
	ds_read2_b32 v[58:59], v16 offset0:64 offset1:80
	ds_read2_b32 v[60:61], v16 offset0:128 offset1:144
	ds_read2_b32 v[62:63], v16 offset0:192 offset1:208
	ds_read2_b32 v[46:47], v32 offset0:32 offset1:48
	ds_read2_b32 v[44:45], v32 offset0:96 offset1:112
	ds_read2_b32 v[42:43], v32 offset0:160 offset1:176
	ds_read2_b32 v[40:41], v32 offset0:224 offset1:240
	ds_read2_b32 v[38:39], v16 offset0:32 offset1:48
	ds_read2_b32 v[36:37], v16 offset0:96 offset1:112
	ds_read2_b32 v[34:35], v16 offset0:160 offset1:176
	ds_read2_b32 v[32:33], v16 offset0:224 offset1:240
	s_waitcnt lgkmcnt(14)
	v_mov_b32_e32 v64, v25
	v_mov_b32_e32 v65, v24
	v_mov_b32_e32 v24, v51
	v_mov_b32_e32 v25, v50
	s_waitcnt lgkmcnt(13)
	v_mov_b32_e32 v50, v53
	v_mov_b32_e32 v51, v52
	s_waitcnt lgkmcnt(12)
	v_mov_b32_e32 v52, v55
	v_mov_b32_e32 v53, v54
	s_waitcnt lgkmcnt(11)
	v_mov_b32_e32 v54, v57
	v_mov_b32_e32 v55, v56
	s_waitcnt lgkmcnt(10)
	v_mov_b32_e32 v56, v59
	v_mov_b32_e32 v57, v58
	s_waitcnt lgkmcnt(9)
	v_mov_b32_e32 v58, v61
	v_mov_b32_e32 v59, v60
	s_waitcnt lgkmcnt(8)
	v_mov_b32_e32 v60, v63
	v_mov_b32_e32 v61, v62
	v_pk_add_f32 v[62:63], v[64:65], 0 op_sel_hi:[1,0]
	s_mov_b32 s0, 0x358637bd
	v_pk_add_f32 v[24:25], v[62:63], v[24:25]
	v_mov_b64_e32 v[30:31], s[0:1]
	v_pk_add_f32 v[24:25], v[24:25], v[50:51]
	s_brev_b32 s10, 60
	v_pk_add_f32 v[24:25], v[24:25], v[52:53]
	s_add_u32 s0, s61, s9
	v_pk_add_f32 v[24:25], v[24:25], v[54:55]
	v_readlane_b32 s1, v253, 31
	v_pk_add_f32 v[24:25], v[24:25], v[56:57]
	v_mov_b32_e32 v23, s13
	v_pk_add_f32 v[24:25], v[24:25], v[58:59]
	s_addc_u32 s1, s1, 0
	v_pk_add_f32 v[24:25], v[24:25], v[60:61]
	v_readlane_b32 s77, v252, 21
	v_pk_fma_f32 v[50:51], v[24:25], s[10:11], v[30:31] op_sel_hi:[1,0,0]
	v_lshl_add_u64 v[24:25], s[0:1], 0, v[26:27]
	v_mul_f32_e32 v16, 0x4b800000, v51
	v_cmp_gt_f32_e32 vcc, s33, v51
	v_readlane_b32 s78, v252, 22
	v_readlane_b32 s79, v252, 23
	v_cndmask_b32_e32 v16, v51, v16, vcc
	v_rsq_f32_e32 v16, v16
	v_readlane_b32 s80, v252, 24
	v_readlane_b32 s81, v252, 25
	v_readlane_b32 s82, v252, 26
	v_mul_f32_e32 v51, 0x45800000, v16
	v_cndmask_b32_e32 v16, v16, v51, vcc
	v_pk_mul_f32 v[12:13], v[12:13], v[16:17] op_sel_hi:[1,0]
	v_pk_mul_f32 v[14:15], v[14:15], v[16:17] op_sel_hi:[1,0]
	v_cmp_gt_f32_e32 vcc, s33, v50
	v_readlane_b32 s83, v252, 27
	v_readlane_b32 s86, v252, 30
	v_readlane_b32 s87, v252, 31
	v_readlane_b32 s88, v252, 32
	v_readlane_b32 s89, v252, 33
	v_readlane_b32 s90, v252, 34
	v_readlane_b32 s91, v252, 35
	s_waitcnt vmcnt(0)
; __device__ __forceinline__ unsigned pk2(float lo, float hi) { return pg8::cvt_pk_bf16(lo, hi); }
; __device__ __forceinline__ float siluf(float x) { return x * __builtin_amdgcn_rcpf(1.0f + __expf(-x)); }
; template <int TY> __device__ __forceinline__ void mc_item(const Params& p, ldsp lds, int item) {
;     ...
;     for (int ei = 0; ei < ET; ++ei) { const int e0 = 16 * (wave * ET + ei) + 4 * q4; const f32x4 w4 = *(const f32x4*)(nwp + e0);
; #pragma unroll
;         for (int tk = 0; tk < 4; ++tk) { const size_t row = (size_t)row0 + 16 * tk + l15;
;             const u32x2 gw = *(const u32x2*)(Pb + row * PP + goff + e0);
;             const float g0 = bf2f(gw.x & 0xffffu), g1 = bf2f(gw.x >> 16), g2 = bf2f(gw.y & 0xffffu), g3 = bf2f(gw.y >> 16);
;             const f32x4 v = acc[ei][tk] * rstd[tk] * w4;
;             float y0 = v[0] * siluf(g0), y1 = v[1] * siluf(g1), y2 = v[2] * siluf(g2), y3 = v[3] * siluf(g3);
;     ...
;             if (!(fabsf(y0) < 1e30f)) y0 = 0.f; if (!(fabsf(y1) < 1e30f)) y1 = 0.f; if (!(fabsf(y2) < 1e30f)) y2 = 0.f; if (!(fabsf(y3) < 1e30f)) y3 = 0.f;
;     ...
;             u32x2 o; o.x = pk2(y0, y1); o.y = pk2(y2, y3);
;             *(u32x2*)(Y + row * LDY + ycol + e0) = o; } }
	v_lshlrev_b32_e32 v16, 16, v48
	v_mul_f32_e32 v52, 0xbfb8aa3b, v16
	v_exp_f32_e32 v52, v52
	v_and_b32_e32 v48, 0xffff0000, v48
	v_lshlrev_b32_e32 v51, 16, v49
	v_and_b32_e32 v49, 0xffff0000, v49
	v_mul_f32_e32 v53, 0xbfb8aa3b, v48
	v_mul_f32_e32 v54, 0xbfb8aa3b, v51
	v_mul_f32_e32 v55, 0xbfb8aa3b, v49
	v_exp_f32_e32 v53, v53
	v_add_f32_e32 v52, 1.0, v52
	v_exp_f32_e32 v54, v54
	v_exp_f32_e32 v55, v55
	v_rcp_f32_e32 v52, v52
	v_add_f32_e32 v53, 1.0, v53
	v_pk_mul_f32 v[12:13], v[12:13], v[18:19]
	v_add_f32_e32 v54, 1.0, v54
	v_rcp_f32_e32 v53, v53
	v_add_f32_e32 v55, 1.0, v55
	v_mul_f32_e32 v16, v52, v16
	v_rcp_f32_e32 v54, v54
	v_mul_f32_e32 v12, v12, v16
	v_rcp_f32_e32 v16, v55
	v_mul_f32_e32 v48, v53, v48
	v_pk_mul_f32 v[14:15], v[14:15], v[20:21]
	v_mul_f32_e32 v13, v13, v48
	v_mul_f32_e32 v48, v54, v51
	v_mul_f32_e32 v16, v16, v49
	v_mul_f32_e32 v14, v14, v48
	v_mul_f32_e32 v15, v15, v16
	v_cvt_pk_bf16_f32 v12, v12, v13
	v_cvt_pk_bf16_f32 v13, v14, v15
	v_lshlrev_b64 v[14:15], 11, v[22:23]
	v_lshl_add_u64 v[14:15], v[24:25], 0, v[14:15]
	global_store_dwordx2 v[14:15], v[12:13], off nt
	v_or_b32_e32 v12, 16, v22
	v_mad_i64_i32 v[14:15], s[0:1], v12, s55, v[28:29]
	v_lshl_add_u64 v[14:15], v[14:15], 0, v[26:27]
	v_mul_f32_e32 v16, 0x4b800000, v50
	v_cndmask_b32_e32 v16, v50, v16, vcc
	v_rsq_f32_e32 v16, v16
	v_mov_b32_e32 v13, s13
	v_or_b32_e32 v48, 32, v22
	v_lshlrev_b64 v[12:13], 11, v[12:13]
	v_mul_f32_e32 v49, 0x45800000, v16
	v_cndmask_b32_e32 v16, v16, v49, vcc
	v_pk_mul_f32 v[8:9], v[8:9], v[16:17] op_sel_hi:[1,0]
	v_pk_mul_f32 v[10:11], v[10:11], v[16:17] op_sel_hi:[1,0]
	v_pk_mul_f32 v[8:9], v[8:9], v[18:19]
	v_mad_i64_i32 v[50:51], s[0:1], v48, s55, v[28:29]
	v_lshl_add_u64 v[12:13], v[24:25], 0, v[12:13]
	v_pk_mul_f32 v[10:11], v[10:11], v[20:21]
	v_lshl_add_u64 v[50:51], v[50:51], 0, v[26:27]
	v_or_b32_e32 v22, 48, v22
	v_lshlrev_b32_e32 v16, 16, v144
	v_and_b32_e32 v14, 0xffff0000, v144
	v_lshlrev_b32_e32 v49, 16, v145
	v_and_b32_e32 v15, 0xffff0000, v145
	v_mul_f32_e32 v52, 0xbfb8aa3b, v16
	v_mul_f32_e32 v53, 0xbfb8aa3b, v14
	v_mul_f32_e32 v54, 0xbfb8aa3b, v49
	v_mul_f32_e32 v55, 0xbfb8aa3b, v15
	v_exp_f32_e32 v52, v52
	v_exp_f32_e32 v53, v53
	v_exp_f32_e32 v54, v54
	v_exp_f32_e32 v55, v55
	v_add_f32_e32 v52, 1.0, v52
	v_add_f32_e32 v53, 1.0, v53
	v_add_f32_e32 v54, 1.0, v54
	v_add_f32_e32 v55, 1.0, v55
	v_rcp_f32_e32 v52, v52
	v_rcp_f32_e32 v53, v53
	v_rcp_f32_e32 v54, v54
	v_rcp_f32_e32 v55, v55
	v_mul_f32_e32 v16, v52, v16
	v_mul_f32_e32 v14, v53, v14
	v_mul_f32_e32 v49, v54, v49
	v_mul_f32_e32 v15, v55, v15
	v_mul_f32_e32 v8, v8, v16
	v_mul_f32_e32 v9, v9, v14
	v_mul_f32_e32 v10, v10, v49
	v_mul_f32_e32 v11, v11, v15
	v_cvt_pk_bf16_f32 v8, v8, v9
	v_cvt_pk_bf16_f32 v9, v10, v11
	global_store_dwordx2 v[12:13], v[8:9], off nt
	s_waitcnt lgkmcnt(7)
	v_mov_b32_e32 v12, v47
	v_mov_b32_e32 v13, v46
	s_waitcnt lgkmcnt(6)
	v_mov_b32_e32 v14, v45
	v_mov_b32_e32 v15, v44
	v_pk_add_f32 v[12:13], v[12:13], 0 op_sel_hi:[1,0]
	s_waitcnt lgkmcnt(5)
	v_mov_b32_e32 v44, v43
	v_mov_b32_e32 v45, v42
	v_pk_add_f32 v[12:13], v[12:13], v[14:15]
	s_waitcnt lgkmcnt(4)
	v_mov_b32_e32 v42, v41
	v_mov_b32_e32 v43, v40
	v_pk_add_f32 v[12:13], v[12:13], v[44:45]
	s_waitcnt lgkmcnt(3)
	v_mov_b32_e32 v40, v39
	v_mov_b32_e32 v41, v38
	v_pk_add_f32 v[12:13], v[12:13], v[42:43]
	s_waitcnt lgkmcnt(2)
	v_mov_b32_e32 v38, v37
	v_mov_b32_e32 v39, v36
	v_pk_add_f32 v[12:13], v[12:13], v[40:41]
	s_waitcnt lgkmcnt(1)
	v_mov_b32_e32 v36, v35
	v_mov_b32_e32 v37, v34
	v_pk_add_f32 v[12:13], v[12:13], v[38:39]
	s_waitcnt lgkmcnt(0)
	v_mov_b32_e32 v34, v33
	v_mov_b32_e32 v35, v32
	v_pk_add_f32 v[12:13], v[12:13], v[36:37]
	v_mov_b32_e32 v49, s13
	v_pk_add_f32 v[12:13], v[12:13], v[34:35]
	v_lshlrev_b64 v[10:11], 11, v[48:49]
	v_pk_fma_f32 v[12:13], v[12:13], s[10:11], v[30:31] op_sel_hi:[1,0,0]
	v_lshl_add_u64 v[10:11], v[24:25], 0, v[10:11]
	v_mul_f32_e32 v14, 0x4b800000, v13
	v_cmp_gt_f32_e32 vcc, s33, v13
	s_nop 1
	v_cndmask_b32_e32 v13, v13, v14, vcc
	v_rsq_f32_e32 v13, v13
	v_mad_i64_i32 v[14:15], s[0:1], v22, s55, v[28:29]
	v_lshl_add_u64 v[14:15], v[14:15], 0, v[26:27]
	v_mul_f32_e32 v16, 0x45800000, v13
	v_cndmask_b32_e32 v16, v13, v16, vcc
	v_pk_mul_f32 v[4:5], v[4:5], v[16:17] op_sel_hi:[1,0]
	v_pk_mul_f32 v[6:7], v[6:7], v[16:17] op_sel_hi:[1,0]
	v_pk_mul_f32 v[4:5], v[18:19], v[4:5]
	v_pk_mul_f32 v[6:7], v[20:21], v[6:7]
	v_cmp_gt_f32_e32 vcc, s33, v12
	v_lshlrev_b32_e32 v13, 16, v154
	v_and_b32_e32 v8, 0xffff0000, v154
	v_lshlrev_b32_e32 v16, 16, v155
	v_and_b32_e32 v9, 0xffff0000, v155
	v_mul_f32_e32 v26, 0xbfb8aa3b, v13
	v_mul_f32_e32 v27, 0xbfb8aa3b, v8
	v_mul_f32_e32 v28, 0xbfb8aa3b, v16
	v_mul_f32_e32 v29, 0xbfb8aa3b, v9
	v_exp_f32_e32 v26, v26
	v_exp_f32_e32 v27, v27
	v_exp_f32_e32 v28, v28
	v_exp_f32_e32 v29, v29
	v_add_f32_e32 v26, 1.0, v26
	v_add_f32_e32 v27, 1.0, v27
	v_add_f32_e32 v28, 1.0, v28
	v_add_f32_e32 v29, 1.0, v29
	v_rcp_f32_e32 v26, v26
	v_rcp_f32_e32 v27, v27
	v_rcp_f32_e32 v28, v28
	v_rcp_f32_e32 v29, v29
	v_mul_f32_e32 v13, v26, v13
	v_mul_f32_e32 v8, v27, v8
	v_mul_f32_e32 v16, v28, v16
	v_mul_f32_e32 v9, v29, v9
	v_mul_f32_e32 v4, v4, v13
	v_mul_f32_e32 v5, v5, v8
	v_mul_f32_e32 v6, v6, v16
	v_mul_f32_e32 v7, v7, v9
	v_cvt_pk_bf16_f32 v4, v4, v5
	v_cvt_pk_bf16_f32 v5, v6, v7
	global_store_dwordx2 v[10:11], v[4:5], off nt
	v_mul_f32_e32 v6, 0x4b800000, v12
	v_cndmask_b32_e32 v6, v12, v6, vcc
	v_rsq_f32_e32 v8, v6
	v_lshlrev_b64 v[6:7], 11, v[22:23]
	v_mul_f32_e32 v9, 0x45800000, v8
	v_cndmask_b32_e32 v8, v8, v9, vcc
	v_pk_mul_f32 v[0:1], v[0:1], v[8:9] op_sel_hi:[1,0]
	v_pk_mul_f32 v[2:3], v[2:3], v[8:9] op_sel_hi:[1,0]
	v_pk_mul_f32 v[0:1], v[18:19], v[0:1]
	v_pk_mul_f32 v[2:3], v[20:21], v[2:3]
	v_lshlrev_b32_e32 v8, 16, v168
	v_and_b32_e32 v4, 0xffff0000, v168
	v_lshlrev_b32_e32 v9, 16, v169
	v_and_b32_e32 v5, 0xffff0000, v169
	v_mul_f32_e32 v10, 0xbfb8aa3b, v8
	v_mul_f32_e32 v11, 0xbfb8aa3b, v4
	v_mul_f32_e32 v12, 0xbfb8aa3b, v9
	v_mul_f32_e32 v13, 0xbfb8aa3b, v5
	v_exp_f32_e32 v10, v10
	v_exp_f32_e32 v11, v11
	v_exp_f32_e32 v12, v12
	v_exp_f32_e32 v13, v13
	v_add_f32_e32 v10, 1.0, v10
	v_add_f32_e32 v11, 1.0, v11
	v_add_f32_e32 v12, 1.0, v12
	v_add_f32_e32 v13, 1.0, v13
	v_rcp_f32_e32 v10, v10
	v_rcp_f32_e32 v11, v11
	v_rcp_f32_e32 v12, v12
	v_rcp_f32_e32 v13, v13
	v_mul_f32_e32 v8, v10, v8
	v_mul_f32_e32 v4, v11, v4
	v_mul_f32_e32 v9, v12, v9
	v_mul_f32_e32 v5, v13, v5
	v_mul_f32_e32 v0, v0, v8
	v_mul_f32_e32 v1, v1, v4
	v_mul_f32_e32 v2, v2, v9
	v_mul_f32_e32 v3, v3, v5
	v_cvt_pk_bf16_f32 v0, v0, v1
	v_cvt_pk_bf16_f32 v1, v2, v3
	v_lshl_add_u64 v[2:3], v[24:25], 0, v[6:7]
	global_store_dwordx2 v[2:3], v[0:1], off nt
	s_waitcnt vmcnt(0) lgkmcnt(0)
	s_barrier

; #define BSYNC() do { asm volatile("s_waitcnt vmcnt(0) lgkmcnt(0)" ::: "memory"); __syncthreads(); } while (0)
; template <int TY> __device__ __forceinline__ void mc_item(const Params& p, ldsp lds, int item) {
;     ...
;     BSYNC();
; #pragma unroll
;     for (int tk = 0; tk < 4; ++tk) { float s = 0.f;
; #pragma unroll
;         for (int w = 0; w < 8; ++w) s += RED[w * 64 + 16 * tk + l15];
;         rstd[tk] = rsqrtf(s * (1.0f / DV) + EPS); }
;     const float* nwp = TY == 0 ? p.in[12] : (TY == 1 ? p.in[14] : p.in[17]);
;     const int goff = TY == 0 ? E_RA + h * 128 : (TY == 1 ? E_GB + h * 128 : O_G + h * 512);
;     constexpr int LDY = TY == 2 ? 2048 : 1024; const int ycol = TY == 0 ? h * 128 : (TY == 1 ? 512 + h * 128 : h * 512);
;     bf16_t* Y = (bf16_t*)(p.ws + WS_Y);
; #pragma unroll
;     for (int ei = 0; ei < ET; ++ei) { const int e0 = 16 * (wave * ET + ei) + 4 * q4; const f32x4 w4 = *(const f32x4*)(nwp + e0);
; #pragma unroll
;         for (int tk = 0; tk < 4; ++tk) { const size_t row = (size_t)row0 + 16 * tk + l15;
;             const u32x2 gw = *(const u32x2*)(Pb + row * PP + goff + e0);
.LBB0_1281:
	s_or_b64 exec, exec, s[0:1]
	v_lshl_add_u32 v8, v23, 2, 0
	v_add_u32_e32 v16, 0x13800, v8
	s_waitcnt vmcnt(0) lgkmcnt(0)
	s_waitcnt lgkmcnt(0)
	s_barrier
	ds_read2_b32 v[8:9], v16 offset1:16
	ds_read2_b32 v[10:11], v16 offset0:64 offset1:80
	ds_read2_b32 v[26:27], v16 offset0:128 offset1:144
	ds_read2_b32 v[28:29], v16 offset0:192 offset1:208
	v_add_u32_e32 v22, 0x400, v16
	s_waitcnt lgkmcnt(3)
	v_mov_b32_e32 v38, v9
	v_mov_b32_e32 v39, v8
	v_pk_add_f32 v[8:9], v[38:39], 0 op_sel_hi:[1,0]
	s_waitcnt lgkmcnt(2)
	v_mov_b32_e32 v38, v11
	v_mov_b32_e32 v39, v10
	ds_read2_b32 v[30:31], v22 offset1:16
	ds_read2_b32 v[32:33], v22 offset0:64 offset1:80
	ds_read2_b32 v[34:35], v22 offset0:128 offset1:144
	ds_read2_b32 v[36:37], v22 offset0:192 offset1:208
	v_pk_add_f32 v[8:9], v[8:9], v[38:39]
	s_waitcnt lgkmcnt(5)
	v_mov_b32_e32 v10, v27
	v_mov_b32_e32 v11, v26
	v_pk_add_f32 v[8:9], v[8:9], v[10:11]
	s_waitcnt lgkmcnt(4)
	v_mov_b32_e32 v10, v29
	v_mov_b32_e32 v11, v28
	v_pk_add_f32 v[8:9], v[8:9], v[10:11]
	s_waitcnt lgkmcnt(3)
	v_mov_b32_e32 v10, v31
	v_mov_b32_e32 v11, v30
	v_pk_add_f32 v[8:9], v[8:9], v[10:11]
	s_waitcnt lgkmcnt(2)
	v_mov_b32_e32 v10, v33
	v_mov_b32_e32 v11, v32
	v_pk_add_f32 v[8:9], v[8:9], v[10:11]
	s_waitcnt lgkmcnt(1)
	v_mov_b32_e32 v10, v35
	v_mov_b32_e32 v11, v34
	v_pk_add_f32 v[8:9], v[8:9], v[10:11]
	s_waitcnt lgkmcnt(0)
	v_mov_b32_e32 v10, v37
	v_mov_b32_e32 v11, v36
	s_mov_b32 s0, 0x358637bd
	v_pk_add_f32 v[8:9], v[8:9], v[10:11]
	v_mov_b64_e32 v[10:11], s[0:1]
	s_brev_b32 s12, 60
	v_pk_fma_f32 v[8:9], v[8:9], s[12:13], v[10:11] op_sel_hi:[1,0,0]
	v_or_b32_e32 v24, s11, v24
	v_mul_f32_e32 v25, 0x4b800000, v9
	v_cmp_gt_f32_e64 s[0:1], s33, v9
	v_cmp_gt_f32_e32 vcc, s33, v8
	v_readlane_b32 s76, v252, 20
	v_cndmask_b32_e64 v9, v9, v25, s[0:1]
	v_rsq_f32_e32 v9, v9
	v_readlane_b32 s88, v252, 32
	v_readlane_b32 s89, v252, 33
	v_readlane_b32 s77, v252, 21
	v_mul_f32_e32 v25, 0x45800000, v9
	v_cndmask_b32_e64 v32, v9, v25, s[0:1]
	v_mul_f32_e32 v9, 0x4b800000, v8
	v_cndmask_b32_e32 v8, v8, v9, vcc
	v_rsq_f32_e32 v8, v8
	v_ashrrev_i32_e32 v25, 31, v24
	v_readlane_b32 s78, v252, 22
	v_readlane_b32 s79, v252, 23
	v_mul_f32_e32 v9, 0x45800000, v8
	v_cndmask_b32_e32 v30, v8, v9, vcc
	ds_read2_b32 v[8:9], v16 offset0:32 offset1:48
	ds_read2_b32 v[26:27], v16 offset0:96 offset1:112
	ds_read2_b32 v[28:29], v16 offset0:160 offset1:176
	ds_read2_b32 v[34:35], v16 offset0:224 offset1:240
	ds_read2_b32 v[36:37], v22 offset0:32 offset1:48
	ds_read2_b32 v[38:39], v22 offset0:96 offset1:112
	ds_read2_b32 v[40:41], v22 offset0:160 offset1:176
	ds_read2_b32 v[42:43], v22 offset0:224 offset1:240
	s_waitcnt lgkmcnt(7)
	v_mov_b32_e32 v44, v9
	v_mov_b32_e32 v45, v8
	v_pk_add_f32 v[8:9], v[44:45], 0 op_sel_hi:[1,0]
	s_waitcnt lgkmcnt(6)
	v_mov_b32_e32 v44, v27
	v_mov_b32_e32 v45, v26
	v_pk_add_f32 v[8:9], v[8:9], v[44:45]
	s_waitcnt lgkmcnt(5)
	v_mov_b32_e32 v26, v29
	v_mov_b32_e32 v27, v28
	v_pk_add_f32 v[8:9], v[8:9], v[26:27]
	s_waitcnt lgkmcnt(4)
	v_mov_b32_e32 v26, v35
	v_mov_b32_e32 v27, v34
	v_pk_add_f32 v[8:9], v[8:9], v[26:27]
	s_waitcnt lgkmcnt(3)
	v_mov_b32_e32 v26, v37
	v_mov_b32_e32 v27, v36
	v_pk_add_f32 v[8:9], v[8:9], v[26:27]
	s_waitcnt lgkmcnt(2)
	v_mov_b32_e32 v26, v39
	v_mov_b32_e32 v27, v38
	v_pk_add_f32 v[8:9], v[8:9], v[26:27]
	s_waitcnt lgkmcnt(1)
	v_mov_b32_e32 v26, v41
	v_mov_b32_e32 v27, v40
	v_pk_add_f32 v[8:9], v[8:9], v[26:27]
	s_waitcnt lgkmcnt(0)
	v_mov_b32_e32 v26, v43
	v_mov_b32_e32 v27, v42
	v_pk_add_f32 v[8:9], v[8:9], v[26:27]
	v_or_b32_e32 v16, s9, v23
	v_pk_fma_f32 v[8:9], v[8:9], s[12:13], v[10:11] op_sel_hi:[1,0,0]
	s_add_u32 s12, s26, s10
	v_mul_f32_e32 v10, 0x4b800000, v9
	v_cmp_gt_f32_e64 s[0:1], s33, v9
	v_cmp_gt_f32_e32 vcc, s33, v8
	s_addc_u32 s13, s27, 0
	v_cndmask_b32_e64 v9, v9, v10, s[0:1]
	v_rsq_f32_e32 v9, v9
	v_mov_b64_e32 v[28:29], s[12:13]
	s_mov_b32 s9, 0x1ec21000
	v_readlane_b32 s80, v252, 24
	v_mul_f32_e32 v10, 0x45800000, v9
	v_cndmask_b32_e64 v26, v9, v10, s[0:1]
	v_mul_f32_e32 v9, 0x4b800000, v8
	v_cndmask_b32_e32 v8, v8, v9, vcc
	v_rsq_f32_e32 v8, v8
	s_add_u32 s0, s68, s10
	v_mad_u64_u32 v[34:35], s[10:11], v16, s55, v[28:29]
	v_mul_f32_e32 v9, 0x45800000, v8
	v_cndmask_b32_e32 v22, v8, v9, vcc
	v_lshl_add_u64 v[8:9], v[24:25], 2, s[88:89]
	v_lshlrev_b64 v[24:25], 1, v[24:25]
	v_lshl_add_u64 v[34:35], v[34:35], 0, v[24:25]
	v_add_co_u32_e32 v34, vcc, s57, v34
	global_load_dwordx4 v[8:11], v[8:9], off
	s_nop 0
	v_addc_co_u32_e32 v35, vcc, 0, v35, vcc
	global_load_dwordx2 v[34:35], v[34:35], off offset:2048
	s_mov_b32 s98, s57
	s_mov_b32 s99, 0
	v_or_b32_e32 v64, 16, v16
	v_mad_u64_u32 v[134:135], s[10:11], v64, s55, v[28:29]
	v_lshl_add_u64 v[140:141], v[134:135], 0, v[24:25]
	v_lshl_add_u64 v[142:143], v[140:141], 0, s[98:99]
	global_load_dwordx2 v[144:145], v[142:143], off offset:2048
	v_or_b32_e32 v146, 32, v16
	v_mad_u64_u32 v[148:149], s[10:11], v146, s55, v[28:29]
	v_lshl_add_u64 v[150:151], v[148:149], 0, v[24:25]
	v_lshl_add_u64 v[152:153], v[150:151], 0, s[98:99]
	global_load_dwordx2 v[154:155], v[152:153], off offset:2048
	v_or_b32_e32 v156, 48, v16
	v_mad_u64_u32 v[166:167], s[10:11], v156, s55, v[28:29]
	v_lshl_add_u64 v[168:169], v[166:167], 0, v[24:25]
	v_lshl_add_u64 v[172:173], v[168:169], 0, s[98:99]
	global_load_dwordx2 v[174:175], v[172:173], off offset:2048
	s_addc_u32 s1, s69, 0
	v_readlane_b32 s81, v252, 25
	v_readlane_b32 s82, v252, 26
	v_readlane_b32 s83, v252, 27
	v_readlane_b32 s84, v252, 28
	v_readlane_b32 s85, v252, 29
	v_readlane_b32 s86, v252, 30
	v_readlane_b32 s87, v252, 31
	v_readlane_b32 s90, v252, 34
	v_readlane_b32 s91, v252, 35
	s_waitcnt vmcnt(0)
; __device__ __forceinline__ unsigned pk2(float lo, float hi) { return pg8::cvt_pk_bf16(lo, hi); }
; __device__ __forceinline__ float siluf(float x) { return x * __builtin_amdgcn_rcpf(1.0f + __expf(-x)); }
; template <int TY> __device__ __forceinline__ void mc_item(const Params& p, ldsp lds, int item) {
;     ...
;     for (int ei = 0; ei < ET; ++ei) { const int e0 = 16 * (wave * ET + ei) + 4 * q4; const f32x4 w4 = *(const f32x4*)(nwp + e0);
; #pragma unroll
;         for (int tk = 0; tk < 4; ++tk) { const size_t row = (size_t)row0 + 16 * tk + l15;
;             const u32x2 gw = *(const u32x2*)(Pb + row * PP + goff + e0);
;             const float g0 = bf2f(gw.x & 0xffffu), g1 = bf2f(gw.x >> 16), g2 = bf2f(gw.y & 0xffffu), g3 = bf2f(gw.y >> 16);
;             const f32x4 v = acc[ei][tk] * rstd[tk] * w4;
;             float y0 = v[0] * siluf(g0), y1 = v[1] * siluf(g1), y2 = v[2] * siluf(g2), y3 = v[3] * siluf(g3);
;     ...
;             if (!(fabsf(y0) < 1e30f)) y0 = 0.f; if (!(fabsf(y1) < 1e30f)) y1 = 0.f; if (!(fabsf(y2) < 1e30f)) y2 = 0.f; if (!(fabsf(y3) < 1e30f)) y3 = 0.f;
;     ...
;             u32x2 o; o.x = pk2(y0, y1); o.y = pk2(y2, y3);
;             *(u32x2*)(Y + row * LDY + ycol + e0) = o; } }
	v_lshlrev_b32_e32 v23, 16, v34
	v_and_b32_e32 v33, 0xffff0000, v35
	v_pk_mul_f32 v[18:19], v[18:19], v[32:33] op_sel_hi:[1,0]
	v_pk_mul_f32 v[20:21], v[20:21], v[32:33] op_sel_hi:[1,0]
	v_mul_f32_e32 v32, 0xbfb8aa3b, v23
	v_exp_f32_e32 v32, v32
	v_and_b32_e32 v27, 0xffff0000, v34
	v_pk_mul_f32 v[18:19], v[18:19], v[8:9]
	v_lshlrev_b32_e32 v31, 16, v35
	v_add_f32_e32 v32, 1.0, v32
	v_rcp_f32_e32 v32, v32
	v_pk_mul_f32 v[20:21], v[20:21], v[10:11]
	v_pk_mul_f32 v[12:13], v[12:13], v[30:31] op_sel_hi:[1,0]
	v_pk_mul_f32 v[14:15], v[14:15], v[30:31] op_sel_hi:[1,0]
	v_mul_f32_e32 v23, v32, v23
	v_mul_f32_e32 v18, v18, v23
	v_mul_f32_e32 v23, 0xbfb8aa3b, v27
	v_exp_f32_e32 v23, v23
	v_pk_mul_f32 v[12:13], v[12:13], v[8:9]
	v_pk_mul_f32 v[14:15], v[14:15], v[10:11]
	v_add_f32_e32 v23, 1.0, v23
	v_rcp_f32_e32 v23, v23
	s_nop 0
	v_mul_f32_e32 v23, v23, v27
	v_mul_f32_e32 v19, v19, v23
	v_mul_f32_e32 v23, 0xbfb8aa3b, v31
	v_exp_f32_e32 v23, v23
	v_cvt_pk_bf16_f32 v18, v18, v19
	s_nop 0
	v_add_f32_e32 v23, 1.0, v23
	v_rcp_f32_e32 v23, v23
	s_nop 0
	v_mul_f32_e32 v23, v23, v31
	v_mul_f32_e32 v20, v20, v23
	v_mul_f32_e32 v23, 0xbfb8aa3b, v33
	v_exp_f32_e32 v23, v23
	s_nop 0
	v_add_f32_e32 v23, 1.0, v23
	v_rcp_f32_e32 v23, v23
	s_nop 0
	v_mul_f32_e32 v23, v23, v33
	v_mul_f32_e32 v21, v21, v23
	v_cvt_pk_bf16_f32 v19, v20, v21
	v_lshlrev_b64 v[20:21], 11, v[16:17]
	v_lshl_add_u64 v[20:21], s[0:1], 0, v[20:21]
	v_lshl_add_u64 v[20:21], v[20:21], 0, v[24:25]
	v_add_co_u32_e32 v20, vcc, s9, v20
	s_nop 1
	v_addc_co_u32_e32 v21, vcc, 0, v21, vcc
	global_store_dwordx2 v[20:21], v[18:19], off offset:1024 nt
	v_or_b32_e32 v18, 16, v16
	v_mad_u64_u32 v[20:21], s[10:11], v18, s55, v[28:29]
	v_lshl_add_u64 v[20:21], v[20:21], 0, v[24:25]
	s_nop 0
	v_mov_b32_e32 v19, v17
	s_nop 0
	v_lshl_add_u64 v[20:21], v[20:21], 0, s[98:99]
	v_lshlrev_b32_e32 v23, 16, v144
	v_mul_f32_e32 v30, 0xbfb8aa3b, v23
	v_exp_f32_e32 v30, v30
	v_and_b32_e32 v20, 0xffff0000, v144
	v_lshlrev_b32_e32 v27, 16, v145
	v_and_b32_e32 v21, 0xffff0000, v145
	v_add_f32_e32 v30, 1.0, v30
	v_rcp_f32_e32 v30, v30
	v_pk_mul_f32 v[4:5], v[4:5], v[26:27] op_sel_hi:[1,0]
	v_pk_mul_f32 v[6:7], v[6:7], v[26:27] op_sel_hi:[1,0]
	v_pk_mul_f32 v[4:5], v[8:9], v[4:5]
	v_mul_f32_e32 v23, v30, v23
	v_mul_f32_e32 v12, v12, v23
	v_mul_f32_e32 v23, 0xbfb8aa3b, v20
	v_exp_f32_e32 v23, v23
	v_pk_mul_f32 v[6:7], v[10:11], v[6:7]
	v_add_f32_e32 v23, 1.0, v23
	v_rcp_f32_e32 v23, v23
	s_nop 0
	v_mul_f32_e32 v20, v23, v20
	v_mul_f32_e32 v13, v13, v20
	v_mul_f32_e32 v20, 0xbfb8aa3b, v27
	v_exp_f32_e32 v20, v20
	v_cvt_pk_bf16_f32 v12, v12, v13
	v_pk_mul_f32 v[0:1], v[0:1], v[22:23] op_sel_hi:[1,0]
	v_pk_mul_f32 v[2:3], v[2:3], v[22:23] op_sel_hi:[1,0]
	v_add_f32_e32 v20, 1.0, v20
	v_rcp_f32_e32 v20, v20
	v_pk_mul_f32 v[0:1], v[8:9], v[0:1]
	v_pk_mul_f32 v[2:3], v[10:11], v[2:3]
	v_mul_f32_e32 v20, v20, v27
	v_mul_f32_e32 v14, v14, v20
	v_mul_f32_e32 v20, 0xbfb8aa3b, v21
	v_exp_f32_e32 v20, v20
	s_nop 0
	v_add_f32_e32 v20, 1.0, v20
	v_rcp_f32_e32 v20, v20
	s_nop 0
	v_mul_f32_e32 v20, v20, v21
	v_mul_f32_e32 v15, v15, v20
	v_cvt_pk_bf16_f32 v13, v14, v15
	v_lshlrev_b64 v[14:15], 11, v[18:19]
	v_lshl_add_u64 v[14:15], s[0:1], 0, v[14:15]
	v_lshl_add_u64 v[14:15], v[14:15], 0, v[24:25]
	v_add_co_u32_e32 v14, vcc, s9, v14
	s_nop 1
	v_addc_co_u32_e32 v15, vcc, 0, v15, vcc
	global_store_dwordx2 v[14:15], v[12:13], off offset:1024 nt
	v_or_b32_e32 v12, 32, v16
	v_mad_u64_u32 v[14:15], s[10:11], v12, s55, v[28:29]
	v_lshl_add_u64 v[14:15], v[14:15], 0, v[24:25]
	s_nop 0
	v_mov_b32_e32 v13, v17
	s_nop 0
	v_lshl_add_u64 v[14:15], v[14:15], 0, s[98:99]
	v_or_b32_e32 v16, 48, v16
	v_lshlrev_b32_e32 v18, 16, v154
	v_mul_f32_e32 v20, 0xbfb8aa3b, v18
	v_exp_f32_e32 v20, v20
	v_and_b32_e32 v14, 0xffff0000, v154
	v_lshlrev_b32_e32 v19, 16, v155
	v_and_b32_e32 v15, 0xffff0000, v155
	v_add_f32_e32 v20, 1.0, v20
	v_rcp_f32_e32 v20, v20
	s_nop 0
	v_mul_f32_e32 v18, v20, v18
	v_mul_f32_e32 v4, v4, v18
	v_mul_f32_e32 v18, 0xbfb8aa3b, v14
	v_exp_f32_e32 v18, v18
	s_nop 0
	v_add_f32_e32 v18, 1.0, v18
	v_rcp_f32_e32 v18, v18
	s_nop 0
	v_mul_f32_e32 v14, v18, v14
	v_mul_f32_e32 v5, v5, v14
	v_mul_f32_e32 v14, 0xbfb8aa3b, v19
	v_exp_f32_e32 v14, v14
	v_cvt_pk_bf16_f32 v4, v4, v5
	s_nop 0
	v_add_f32_e32 v14, 1.0, v14
	v_rcp_f32_e32 v14, v14
	s_nop 0
	v_mul_f32_e32 v14, v14, v19
	v_mul_f32_e32 v6, v6, v14
	v_mul_f32_e32 v14, 0xbfb8aa3b, v15
	v_exp_f32_e32 v14, v14
	s_nop 0
	v_add_f32_e32 v14, 1.0, v14
	v_rcp_f32_e32 v14, v14
	s_nop 0
	v_mul_f32_e32 v14, v14, v15
	v_mul_f32_e32 v7, v7, v14
	v_cvt_pk_bf16_f32 v5, v6, v7
	v_lshlrev_b64 v[6:7], 11, v[12:13]
	v_lshl_add_u64 v[6:7], s[0:1], 0, v[6:7]
	v_lshl_add_u64 v[6:7], v[6:7], 0, v[24:25]
	v_add_co_u32_e32 v6, vcc, s9, v6
	s_nop 1
	v_addc_co_u32_e32 v7, vcc, 0, v7, vcc
	global_store_dwordx2 v[6:7], v[4:5], off offset:1024 nt
	v_mad_u64_u32 v[4:5], s[10:11], v16, s55, v[28:29]
	v_lshl_add_u64 v[4:5], v[4:5], 0, v[24:25]
	s_nop 0
	s_nop 1
	v_lshl_add_u64 v[4:5], v[4:5], 0, s[98:99]
	v_lshlrev_b32_e32 v6, 16, v174
	v_mul_f32_e32 v8, 0xbfb8aa3b, v6
	v_exp_f32_e32 v8, v8
	v_and_b32_e32 v4, 0xffff0000, v174
	v_lshlrev_b32_e32 v7, 16, v175
	v_and_b32_e32 v5, 0xffff0000, v175
	v_add_f32_e32 v8, 1.0, v8
	v_rcp_f32_e32 v8, v8
	s_nop 0
	v_mul_f32_e32 v6, v8, v6
	v_mul_f32_e32 v0, v0, v6
	v_mul_f32_e32 v6, 0xbfb8aa3b, v4
	v_exp_f32_e32 v6, v6
	s_nop 0
	v_add_f32_e32 v6, 1.0, v6
	v_rcp_f32_e32 v6, v6
	s_nop 0
	v_mul_f32_e32 v4, v6, v4
	v_mul_f32_e32 v1, v1, v4
	v_mul_f32_e32 v4, 0xbfb8aa3b, v7
	v_exp_f32_e32 v4, v4
	v_cvt_pk_bf16_f32 v0, v0, v1
	s_nop 0
	v_add_f32_e32 v4, 1.0, v4
	v_rcp_f32_e32 v4, v4
	s_nop 0
	v_mul_f32_e32 v4, v4, v7
	v_mul_f32_e32 v2, v2, v4
	v_mul_f32_e32 v4, 0xbfb8aa3b, v5
	v_exp_f32_e32 v4, v4
	s_nop 0
	v_add_f32_e32 v4, 1.0, v4
	v_rcp_f32_e32 v4, v4
	s_nop 0
	v_mul_f32_e32 v4, v4, v5
	v_mul_f32_e32 v3, v3, v4
	v_cvt_pk_bf16_f32 v1, v2, v3
	v_lshlrev_b64 v[2:3], 11, v[16:17]
	v_lshl_add_u64 v[2:3], s[0:1], 0, v[2:3]
	v_lshl_add_u64 v[2:3], v[2:3], 0, v[24:25]
	v_add_co_u32_e32 v2, vcc, 0x1ec21000, v2
	s_nop 1
	v_addc_co_u32_e32 v3, vcc, 0, v3, vcc
	global_store_dwordx2 v[2:3], v[0:1], off offset:1024 nt
	s_waitcnt vmcnt(0) lgkmcnt(0)
	s_barrier
	s_branch .LBB0_1267
